# P5 scan-first parity taken from bx bit 6 instead of bit 5 (same K/V sharing groups)
# speedup vs baseline: 1.0007x; 1.0007x over previous
.LBB0_670:
	v_writelane_b32 v255, s64, 53
	s_cmpk_gt_i32 s16, 0xff
	v_mbcnt_lo_u32_b32 v0, -1, 0
	v_mbcnt_hi_u32_b32 v0, -1, v0
	s_cbranch_scc1 .LBB0_711
	s_bitcmp1_b32 s64, 6
	s_cbranch_scc0 .Lp5_attn_entry
	s_cmp_eq_u32 s98, 0x52
	s_cbranch_scc1 .Lp5_attn_entry
	s_mov_b32 s98, 0x51
	s_mov_b32 s99, s16
	v_readlane_b32 s73, v254, 20
	s_branch .LBB0_711
